# G3 tail workgroups (the 84 with one GEMM unit fewer) read the f32 residual stream XB once at the end of G3 so that G4's gated-residual epilogue finds it in the memory-side cache
# baseline (speedup 1.0000x reference)
.LBB0_1693:
	v_readlane_b32 s0, v253, 59
	v_readlane_b32 s1, v253, 60
	s_andn2_b64 vcc, exec, s[0:1]
	s_cbranch_vccnz .Lpfx_skip
	v_readlane_b32 s2, v250, 2
	s_sub_i32 s2, s2, 0xac
	v_readfirstlane_b32 s3, v0
	s_lshr_b32 s3, s3, 6
	s_lshl_b32 s2, s2, 3
	s_add_i32 s2, s2, s3
	v_readlane_b32 s4, v250, 19
	v_readlane_b32 s5, v250, 20
	s_add_u32 s4, s4, 0x44e00000
	s_addc_u32 s5, s5, 0
	v_and_b32_e32 v2, 63, v0
	v_lshlrev_b32_e32 v2, 7, v2
.Lpfx_loop:
	s_lshl_b32 s6, s2, 13
	s_add_u32 s8, s4, s6
	s_addc_u32 s9, s5, 0
	global_load_dword v3, v2, s[8:9]
	s_addk_i32 s2, 0x2a0
	s_cmpk_lt_i32 s2, 0x2000
	s_cbranch_scc1 .Lpfx_loop
	s_waitcnt vmcnt(0)
